# HGRN2 scan loop rewritten by hand (o/s wave roles, recurrence in registers, 4 sets prefetched), with dnscan2 cvtfix finB finD
# speedup vs baseline: 1.0082x; 1.0082x over previous
; __device__ __forceinline__ int ptid_(int wave) { int l_; asm volatile("v_mbcnt_lo_u32_b32 %0, -1, 0\n\tv_mbcnt_hi_u32_b32 %0, -1, %0" : "=v"(l_)); return (wave << 6) | l_; }
; __device__ void hg_scan_block(const Params& p, int L, int item) {
;   float* misc = (float*)(p.ws + MISC_OFF);
;   bfu* buf = (bfu*)(p.ws + R_OFF);
;   const int bh = item >> 2, qt = item & 3;
;   int tid = ptid_(p.tid); asm volatile("" : "+v"(tid));
;   const int w = tid >> 6, lane = tid & 63, c = lane & 15, q = lane >> 4;
;   const int rt = w >> 1, ct = w & 1, dt = w;
;   bfu* St = (bfu*)smem;
;   const int b = bh >> 2, h = bh & 3;
;   __syncthreads();
;   for (int i = tid; i < 4 * 2176; i += NTHR) St[i] = 0;
;   f32x4 Sacc[2];
;   Sacc[0] = (f32x4){0.f, 0.f, 0.f, 0.f}; Sacc[1] = Sacc[0];
;     ...
;   HG_DECL(A) HG_DECL(B) HG_DECL(C)
.LBB0_264:
	s_or_b64 exec, exec, s[12:13]
	v_mbcnt_lo_u32_b32 v0, -1, 0
	v_mbcnt_hi_u32_b32 v0, -1, v0
	s_lshr_b32 s1, s33, 6
	s_and_b32 s2, s1, 3
	s_lshr_b32 s3, s1, 2
	v_and_b32_e32 v2, 15, v0
	v_lshrrev_b32_e32 v3, 4, v0
	v_mul_u32_u24_e32 v4, 0x2400, v3
	v_lshl_add_u32 v4, v2, 4, v4
	s_and_b32 s12, s0, 3
	s_lshl_b32 s12, s12, 8
	s_mul_i32 s13, s40, 0x2400000
	s_add_u32 s38, s16, s13
	s_addc_u32 s39, s17, 0
	s_add_u32 s38, s38, s12
	s_addc_u32 s39, s39, 0
	s_mov_b32 s18, s38
	s_mov_b32 s19, s39
	s_lshl_b32 s12, s0, 15
	s_add_u32 s36, s52, 0x233000
	s_addc_u32 s37, s53, 0
	s_add_u32 s36, s36, s12
	s_addc_u32 s37, s37, 0
	s_mov_b32 s22, 0
	s_cmp_eq_u32 s3, 1
	s_cbranch_scc1 .Lhg_scan_s
	s_lshl_b32 s12, s2, 2
	s_add_i32 s12, s12, 0
	s_mul_i32 s12, s12, 0x9000
	s_add_i32 s12, s12, 0xc00
	v_add_u32_e32 v144, s12, v4
	s_lshl_b32 s12, s2, 2
	s_add_i32 s12, s12, 1
	s_mul_i32 s12, s12, 0x9000
	s_add_i32 s12, s12, 0xc00
	v_add_u32_e32 v145, s12, v4
	s_lshl_b32 s12, s2, 2
	s_add_i32 s12, s12, 2
	s_mul_i32 s12, s12, 0x9000
	s_add_i32 s12, s12, 0xc00
	v_add_u32_e32 v146, s12, v4
	s_lshl_b32 s12, s2, 2
	s_add_i32 s12, s12, 3
	s_mul_i32 s12, s12, 0x9000
	s_add_i32 s12, s12, 0xc00
	v_add_u32_e32 v147, s12, v4
	v_mul_u32_u24_e32 v5, 0x9000, v3
	v_lshl_add_u32 v5, v2, 1, v5
	s_mul_i32 s12, s2, 0x24000
	s_lshl_b32 s13, s21, 6
	s_add_i32 s12, s12, s13
	s_add_i32 s12, s12, 0x1c00
	v_add_u32_e32 v148, s12, v5
	v_add_u32_e32 v149, 0x2400, v148
	v_add_u32_e32 v150, 0x4800, v148
	v_add_u32_e32 v151, 0x6c00, v148
	v_mul_u32_u24_e32 v5, 0x110, v2
	v_lshl_add_u32 v152, v3, 4, v5
	s_mov_b32 s0, 0
	s_mul_i32 s2, s0, 0x90000
	s_add_u32 s12, s38, s2
	s_addc_u32 s13, s39, 0
	global_load_dwordx4 v[2:5], v144, s[12:13]
	global_load_dwordx4 v[6:9], v145, s[12:13]
	global_load_dwordx4 v[10:13], v146, s[12:13]
	global_load_dwordx4 v[14:17], v147, s[12:13]
	global_load_ushort v18, v148, s[12:13]
	global_load_ushort v19, v149, s[12:13]
	global_load_ushort v20, v150, s[12:13]
	global_load_ushort v21, v151, s[12:13]
	global_load_ushort v22, v148, s[12:13] offset:32
	global_load_ushort v23, v149, s[12:13] offset:32
	global_load_ushort v24, v150, s[12:13] offset:32
	global_load_ushort v25, v151, s[12:13] offset:32
	global_load_dword v153, v1, s[36:37]
	global_load_dword v153, v1, s[36:37]
	global_load_dword v153, v1, s[36:37]
	global_load_dword v153, v1, s[36:37]
	global_load_dword v153, v1, s[36:37]
	global_load_dword v153, v1, s[36:37]
	global_load_dword v153, v1, s[36:37]
	global_load_dword v153, v1, s[36:37]
	s_mov_b32 s0, 1
	s_mul_i32 s2, s0, 0x90000
	s_add_u32 s12, s38, s2
	s_addc_u32 s13, s39, 0
	global_load_dwordx4 v[26:29], v144, s[12:13]
	global_load_dwordx4 v[30:33], v145, s[12:13]
	global_load_dwordx4 v[34:37], v146, s[12:13]
	global_load_dwordx4 v[38:41], v147, s[12:13]
	global_load_ushort v42, v148, s[12:13]
	global_load_ushort v43, v149, s[12:13]
	global_load_ushort v44, v150, s[12:13]
	global_load_ushort v45, v151, s[12:13]
	global_load_ushort v46, v148, s[12:13] offset:32
	global_load_ushort v47, v149, s[12:13] offset:32
	global_load_ushort v48, v150, s[12:13] offset:32
	global_load_ushort v49, v151, s[12:13] offset:32
	global_load_dword v153, v1, s[36:37]
	global_load_dword v153, v1, s[36:37]
	global_load_dword v153, v1, s[36:37]
	global_load_dword v153, v1, s[36:37]
	global_load_dword v153, v1, s[36:37]
	global_load_dword v153, v1, s[36:37]
	global_load_dword v153, v1, s[36:37]
	global_load_dword v153, v1, s[36:37]
	s_mov_b32 s0, 2
	s_mul_i32 s2, s0, 0x90000
	s_add_u32 s12, s38, s2
	s_addc_u32 s13, s39, 0
	global_load_dwordx4 v[50:53], v144, s[12:13]
	global_load_dwordx4 v[54:57], v145, s[12:13]
	global_load_dwordx4 v[58:61], v146, s[12:13]
	global_load_dwordx4 v[62:65], v147, s[12:13]
	global_load_ushort v66, v148, s[12:13]
	global_load_ushort v67, v149, s[12:13]
	global_load_ushort v68, v150, s[12:13]
	global_load_ushort v69, v151, s[12:13]
	global_load_ushort v70, v148, s[12:13] offset:32
	global_load_ushort v71, v149, s[12:13] offset:32
	global_load_ushort v72, v150, s[12:13] offset:32
	global_load_ushort v73, v151, s[12:13] offset:32
	global_load_dword v153, v1, s[36:37]
	global_load_dword v153, v1, s[36:37]
	global_load_dword v153, v1, s[36:37]
	global_load_dword v153, v1, s[36:37]
	global_load_dword v153, v1, s[36:37]
	global_load_dword v153, v1, s[36:37]
	global_load_dword v153, v1, s[36:37]
	global_load_dword v153, v1, s[36:37]
	s_waitcnt lgkmcnt(0)
	s_barrier
.Lhg_scan_loop_o:
	ds_read_b128 v[108:111], v152 offset:0
	ds_read_b128 v[124:127], v152 offset:4352
	ds_read_b128 v[112:115], v152 offset:64
	ds_read_b128 v[128:131], v152 offset:4416
	ds_read_b128 v[116:119], v152 offset:128
	ds_read_b128 v[132:135], v152 offset:4480
	ds_read_b128 v[120:123], v152 offset:192
	ds_read_b128 v[136:139], v152 offset:4544
	s_waitcnt vmcnt(48)
	v_lshlrev_b32_e32 v100, 16, v18
	v_lshlrev_b32_e32 v101, 16, v19
	v_lshlrev_b32_e32 v102, 16, v20
	v_lshlrev_b32_e32 v103, 16, v21
	v_lshlrev_b32_e32 v104, 16, v22
	v_lshlrev_b32_e32 v105, 16, v23
	v_lshlrev_b32_e32 v106, 16, v24
	v_lshlrev_b32_e32 v107, 16, v25
	s_add_i32 s0, s22, 3
	s_min_u32 s0, s0, 63
	s_mul_i32 s2, s0, 0x90000
	s_add_u32 s12, s38, s2
	s_addc_u32 s13, s39, 0
	global_load_dwordx4 v[74:77], v144, s[12:13]
	global_load_dwordx4 v[78:81], v145, s[12:13]
	global_load_dwordx4 v[82:85], v146, s[12:13]
	global_load_dwordx4 v[86:89], v147, s[12:13]
	global_load_ushort v90, v148, s[12:13]
	global_load_ushort v91, v149, s[12:13]
	global_load_ushort v92, v150, s[12:13]
	global_load_ushort v93, v151, s[12:13]
	global_load_ushort v94, v148, s[12:13] offset:32
	global_load_ushort v95, v149, s[12:13] offset:32
	global_load_ushort v96, v150, s[12:13] offset:32
	global_load_ushort v97, v151, s[12:13] offset:32
	s_waitcnt lgkmcnt(7)
	v_mfma_f32_16x16x32_bf16 v[100:103], v[2:5], v[108:111], v[100:103]
	s_waitcnt lgkmcnt(6)
	v_mfma_f32_16x16x32_bf16 v[104:107], v[2:5], v[124:127], v[104:107]
	s_waitcnt lgkmcnt(5)
	v_mfma_f32_16x16x32_bf16 v[100:103], v[6:9], v[112:115], v[100:103]
	s_waitcnt lgkmcnt(4)
	v_mfma_f32_16x16x32_bf16 v[104:107], v[6:9], v[128:131], v[104:107]
	s_waitcnt lgkmcnt(3)
	v_mfma_f32_16x16x32_bf16 v[100:103], v[10:13], v[116:119], v[100:103]
	s_waitcnt lgkmcnt(2)
	v_mfma_f32_16x16x32_bf16 v[104:107], v[10:13], v[132:135], v[104:107]
	s_waitcnt lgkmcnt(1)
	v_mfma_f32_16x16x32_bf16 v[100:103], v[14:17], v[120:123], v[100:103]
	s_waitcnt lgkmcnt(0)
	v_mfma_f32_16x16x32_bf16 v[104:107], v[14:17], v[136:139], v[104:107]
	s_nop 6
	v_cvt_pk_bf16_f32 v140, v100, v101
	v_cvt_pk_bf16_f32 v141, v102, v103
	v_cvt_pk_bf16_f32 v142, v104, v105
	v_cvt_pk_bf16_f32 v143, v106, v107
	global_store_short v148, v140, s[18:19]
	global_store_short_d16_hi v149, v140, s[18:19]
	global_store_short v150, v141, s[18:19]
	global_store_short_d16_hi v151, v141, s[18:19]
	global_store_short v148, v142, s[18:19] offset:32
	global_store_short_d16_hi v149, v142, s[18:19] offset:32
	global_store_short v150, v143, s[18:19] offset:32
	global_store_short_d16_hi v151, v143, s[18:19] offset:32
	s_add_u32 s18, s18, 0x90000
	s_addc_u32 s19, s19, 0
	s_add_i32 s22, s22, 1
	s_barrier
	ds_read_b128 v[108:111], v152 offset:8704
	ds_read_b128 v[124:127], v152 offset:13056
	ds_read_b128 v[112:115], v152 offset:8768
	ds_read_b128 v[128:131], v152 offset:13120
	ds_read_b128 v[116:119], v152 offset:8832
	ds_read_b128 v[132:135], v152 offset:13184
	ds_read_b128 v[120:123], v152 offset:8896
	ds_read_b128 v[136:139], v152 offset:13248
	s_waitcnt vmcnt(48)
	v_lshlrev_b32_e32 v100, 16, v42
	v_lshlrev_b32_e32 v101, 16, v43
	v_lshlrev_b32_e32 v102, 16, v44
	v_lshlrev_b32_e32 v103, 16, v45
	v_lshlrev_b32_e32 v104, 16, v46
	v_lshlrev_b32_e32 v105, 16, v47
	v_lshlrev_b32_e32 v106, 16, v48
	v_lshlrev_b32_e32 v107, 16, v49
	s_add_i32 s0, s22, 3
	s_min_u32 s0, s0, 63
	s_mul_i32 s2, s0, 0x90000
	s_add_u32 s12, s38, s2
	s_addc_u32 s13, s39, 0
	global_load_dwordx4 v[2:5], v144, s[12:13]
	global_load_dwordx4 v[6:9], v145, s[12:13]
	global_load_dwordx4 v[10:13], v146, s[12:13]
	global_load_dwordx4 v[14:17], v147, s[12:13]
	global_load_ushort v18, v148, s[12:13]
	global_load_ushort v19, v149, s[12:13]
	global_load_ushort v20, v150, s[12:13]
	global_load_ushort v21, v151, s[12:13]
	global_load_ushort v22, v148, s[12:13] offset:32
	global_load_ushort v23, v149, s[12:13] offset:32
	global_load_ushort v24, v150, s[12:13] offset:32
	global_load_ushort v25, v151, s[12:13] offset:32
	s_waitcnt lgkmcnt(7)
	v_mfma_f32_16x16x32_bf16 v[100:103], v[26:29], v[108:111], v[100:103]
	s_waitcnt lgkmcnt(6)
	v_mfma_f32_16x16x32_bf16 v[104:107], v[26:29], v[124:127], v[104:107]
	s_waitcnt lgkmcnt(5)
	v_mfma_f32_16x16x32_bf16 v[100:103], v[30:33], v[112:115], v[100:103]
	s_waitcnt lgkmcnt(4)
	v_mfma_f32_16x16x32_bf16 v[104:107], v[30:33], v[128:131], v[104:107]
	s_waitcnt lgkmcnt(3)
	v_mfma_f32_16x16x32_bf16 v[100:103], v[34:37], v[116:119], v[100:103]
	s_waitcnt lgkmcnt(2)
	v_mfma_f32_16x16x32_bf16 v[104:107], v[34:37], v[132:135], v[104:107]
	s_waitcnt lgkmcnt(1)
	v_mfma_f32_16x16x32_bf16 v[100:103], v[38:41], v[120:123], v[100:103]
	s_waitcnt lgkmcnt(0)
	v_mfma_f32_16x16x32_bf16 v[104:107], v[38:41], v[136:139], v[104:107]
	s_nop 6
	v_cvt_pk_bf16_f32 v140, v100, v101
	v_cvt_pk_bf16_f32 v141, v102, v103
	v_cvt_pk_bf16_f32 v142, v104, v105
	v_cvt_pk_bf16_f32 v143, v106, v107
	global_store_short v148, v140, s[18:19]
	global_store_short_d16_hi v149, v140, s[18:19]
	global_store_short v150, v141, s[18:19]
	global_store_short_d16_hi v151, v141, s[18:19]
	global_store_short v148, v142, s[18:19] offset:32
	global_store_short_d16_hi v149, v142, s[18:19] offset:32
	global_store_short v150, v143, s[18:19] offset:32
	global_store_short_d16_hi v151, v143, s[18:19] offset:32
	s_add_u32 s18, s18, 0x90000
	s_addc_u32 s19, s19, 0
	s_add_i32 s22, s22, 1
	s_barrier
	ds_read_b128 v[108:111], v152 offset:0
	ds_read_b128 v[124:127], v152 offset:4352
	ds_read_b128 v[112:115], v152 offset:64
	ds_read_b128 v[128:131], v152 offset:4416
	ds_read_b128 v[116:119], v152 offset:128
	ds_read_b128 v[132:135], v152 offset:4480
	ds_read_b128 v[120:123], v152 offset:192
	ds_read_b128 v[136:139], v152 offset:4544
	s_waitcnt vmcnt(48)
	v_lshlrev_b32_e32 v100, 16, v66
	v_lshlrev_b32_e32 v101, 16, v67
	v_lshlrev_b32_e32 v102, 16, v68
	v_lshlrev_b32_e32 v103, 16, v69
	v_lshlrev_b32_e32 v104, 16, v70
	v_lshlrev_b32_e32 v105, 16, v71
	v_lshlrev_b32_e32 v106, 16, v72
	v_lshlrev_b32_e32 v107, 16, v73
	s_add_i32 s0, s22, 3
	s_min_u32 s0, s0, 63
	s_mul_i32 s2, s0, 0x90000
	s_add_u32 s12, s38, s2
	s_addc_u32 s13, s39, 0
	global_load_dwordx4 v[26:29], v144, s[12:13]
	global_load_dwordx4 v[30:33], v145, s[12:13]
	global_load_dwordx4 v[34:37], v146, s[12:13]
	global_load_dwordx4 v[38:41], v147, s[12:13]
	global_load_ushort v42, v148, s[12:13]
	global_load_ushort v43, v149, s[12:13]
	global_load_ushort v44, v150, s[12:13]
	global_load_ushort v45, v151, s[12:13]
	global_load_ushort v46, v148, s[12:13] offset:32
	global_load_ushort v47, v149, s[12:13] offset:32
	global_load_ushort v48, v150, s[12:13] offset:32
	global_load_ushort v49, v151, s[12:13] offset:32
	s_waitcnt lgkmcnt(7)
	v_mfma_f32_16x16x32_bf16 v[100:103], v[50:53], v[108:111], v[100:103]
	s_waitcnt lgkmcnt(6)
	v_mfma_f32_16x16x32_bf16 v[104:107], v[50:53], v[124:127], v[104:107]
	s_waitcnt lgkmcnt(5)
	v_mfma_f32_16x16x32_bf16 v[100:103], v[54:57], v[112:115], v[100:103]
	s_waitcnt lgkmcnt(4)
	v_mfma_f32_16x16x32_bf16 v[104:107], v[54:57], v[128:131], v[104:107]
	s_waitcnt lgkmcnt(3)
	v_mfma_f32_16x16x32_bf16 v[100:103], v[58:61], v[116:119], v[100:103]
	s_waitcnt lgkmcnt(2)
	v_mfma_f32_16x16x32_bf16 v[104:107], v[58:61], v[132:135], v[104:107]
	s_waitcnt lgkmcnt(1)
	v_mfma_f32_16x16x32_bf16 v[100:103], v[62:65], v[120:123], v[100:103]
	s_waitcnt lgkmcnt(0)
	v_mfma_f32_16x16x32_bf16 v[104:107], v[62:65], v[136:139], v[104:107]
	s_nop 6
	v_cvt_pk_bf16_f32 v140, v100, v101
	v_cvt_pk_bf16_f32 v141, v102, v103
	v_cvt_pk_bf16_f32 v142, v104, v105
	v_cvt_pk_bf16_f32 v143, v106, v107
	global_store_short v148, v140, s[18:19]
	global_store_short_d16_hi v149, v140, s[18:19]
	global_store_short v150, v141, s[18:19]
	global_store_short_d16_hi v151, v141, s[18:19]
	global_store_short v148, v142, s[18:19] offset:32
	global_store_short_d16_hi v149, v142, s[18:19] offset:32
	global_store_short v150, v143, s[18:19] offset:32
	global_store_short_d16_hi v151, v143, s[18:19] offset:32
	s_add_u32 s18, s18, 0x90000
	s_addc_u32 s19, s19, 0
	s_add_i32 s22, s22, 1
	s_barrier
	ds_read_b128 v[108:111], v152 offset:8704
	ds_read_b128 v[124:127], v152 offset:13056
	ds_read_b128 v[112:115], v152 offset:8768
	ds_read_b128 v[128:131], v152 offset:13120
	ds_read_b128 v[116:119], v152 offset:8832
	ds_read_b128 v[132:135], v152 offset:13184
	ds_read_b128 v[120:123], v152 offset:8896
	ds_read_b128 v[136:139], v152 offset:13248
	s_waitcnt vmcnt(48)
	v_lshlrev_b32_e32 v100, 16, v90
	v_lshlrev_b32_e32 v101, 16, v91
	v_lshlrev_b32_e32 v102, 16, v92
	v_lshlrev_b32_e32 v103, 16, v93
	v_lshlrev_b32_e32 v104, 16, v94
	v_lshlrev_b32_e32 v105, 16, v95
	v_lshlrev_b32_e32 v106, 16, v96
	v_lshlrev_b32_e32 v107, 16, v97
	s_add_i32 s0, s22, 3
	s_min_u32 s0, s0, 63
	s_mul_i32 s2, s0, 0x90000
	s_add_u32 s12, s38, s2
	s_addc_u32 s13, s39, 0
	global_load_dwordx4 v[50:53], v144, s[12:13]
	global_load_dwordx4 v[54:57], v145, s[12:13]
	global_load_dwordx4 v[58:61], v146, s[12:13]
	global_load_dwordx4 v[62:65], v147, s[12:13]
	global_load_ushort v66, v148, s[12:13]
	global_load_ushort v67, v149, s[12:13]
	global_load_ushort v68, v150, s[12:13]
	global_load_ushort v69, v151, s[12:13]
	global_load_ushort v70, v148, s[12:13] offset:32
	global_load_ushort v71, v149, s[12:13] offset:32
	global_load_ushort v72, v150, s[12:13] offset:32
	global_load_ushort v73, v151, s[12:13] offset:32
	s_waitcnt lgkmcnt(7)
	v_mfma_f32_16x16x32_bf16 v[100:103], v[74:77], v[108:111], v[100:103]
	s_waitcnt lgkmcnt(6)
	v_mfma_f32_16x16x32_bf16 v[104:107], v[74:77], v[124:127], v[104:107]
	s_waitcnt lgkmcnt(5)
	v_mfma_f32_16x16x32_bf16 v[100:103], v[78:81], v[112:115], v[100:103]
	s_waitcnt lgkmcnt(4)
	v_mfma_f32_16x16x32_bf16 v[104:107], v[78:81], v[128:131], v[104:107]
	s_waitcnt lgkmcnt(3)
	v_mfma_f32_16x16x32_bf16 v[100:103], v[82:85], v[116:119], v[100:103]
	s_waitcnt lgkmcnt(2)
	v_mfma_f32_16x16x32_bf16 v[104:107], v[82:85], v[132:135], v[104:107]
	s_waitcnt lgkmcnt(1)
	v_mfma_f32_16x16x32_bf16 v[100:103], v[86:89], v[120:123], v[100:103]
	s_waitcnt lgkmcnt(0)
	v_mfma_f32_16x16x32_bf16 v[104:107], v[86:89], v[136:139], v[104:107]
	s_nop 6
	v_cvt_pk_bf16_f32 v140, v100, v101
	v_cvt_pk_bf16_f32 v141, v102, v103
	v_cvt_pk_bf16_f32 v142, v104, v105
	v_cvt_pk_bf16_f32 v143, v106, v107
	global_store_short v148, v140, s[18:19]
	global_store_short_d16_hi v149, v140, s[18:19]
	global_store_short v150, v141, s[18:19]
	global_store_short_d16_hi v151, v141, s[18:19]
	global_store_short v148, v142, s[18:19] offset:32
	global_store_short_d16_hi v149, v142, s[18:19] offset:32
	global_store_short v150, v143, s[18:19] offset:32
	global_store_short_d16_hi v151, v143, s[18:19] offset:32
	s_add_u32 s18, s18, 0x90000
	s_addc_u32 s19, s19, 0
	s_add_i32 s22, s22, 1
	s_barrier
	s_cmp_lt_u32 s22, 64
	s_cbranch_scc1 .Lhg_scan_loop_o
	s_branch .LBB0_259
.Lhg_scan_s:
	s_lshl_b32 s12, s2, 2
	s_add_i32 s12, s12, 0
	s_mul_i32 s12, s12, 0x9000
	s_add_i32 s12, s12, 0x1000
	v_add_u32_e32 v188, s12, v4
	s_lshl_b32 s12, s2, 2
	s_add_i32 s12, s12, 1
	s_mul_i32 s12, s12, 0x9000
	s_add_i32 s12, s12, 0x1000
	v_add_u32_e32 v189, s12, v4
	s_lshl_b32 s12, s2, 2
	s_add_i32 s12, s12, 2
	s_mul_i32 s12, s12, 0x9000
	s_add_i32 s12, s12, 0x1000
	v_add_u32_e32 v190, s12, v4
	s_lshl_b32 s12, s2, 2
	s_add_i32 s12, s12, 3
	s_mul_i32 s12, s12, 0x9000
	s_add_i32 s12, s12, 0x1000
	v_add_u32_e32 v191, s12, v4
	s_lshl_b32 s12, s21, 2
	s_add_i32 s12, s12, 0
	s_mul_i32 s12, s12, 0x9000
	s_add_i32 s12, s12, 0x1400
	v_add_u32_e32 v192, s12, v4
	s_lshl_b32 s12, s21, 2
	s_add_i32 s12, s12, 1
	s_mul_i32 s12, s12, 0x9000
	s_add_i32 s12, s12, 0x1400
	v_add_u32_e32 v193, s12, v4
	s_lshl_b32 s12, s21, 2
	s_add_i32 s12, s12, 2
	s_mul_i32 s12, s12, 0x9000
	s_add_i32 s12, s12, 0x1400
	v_add_u32_e32 v194, s12, v4
	s_lshl_b32 s12, s21, 2
	s_add_i32 s12, s12, 3
	s_mul_i32 s12, s12, 0x9000
	s_add_i32 s12, s12, 0x1400
	v_add_u32_e32 v195, s12, v4
	s_lshl_b32 s12, s2, 7
	v_lshl_add_u32 v196, v3, 4, s12
	v_add_u32_e32 v197, 64, v196
	v_mul_u32_u24_e32 v5, 0x110, v2
	v_lshl_add_u32 v5, v3, 3, v5
	s_lshl_b32 s12, s2, 6
	v_add_u32_e32 v198, s12, v5
	v_mov_b32_e32 v164, 0
	v_mov_b32_e32 v165, 0
	v_mov_b32_e32 v166, 0
	v_mov_b32_e32 v167, 0
	v_mov_b32_e32 v168, 0
	v_mov_b32_e32 v169, 0
	v_mov_b32_e32 v170, 0
	v_mov_b32_e32 v171, 0
	v_mov_b32_e32 v172, 0
	v_mov_b32_e32 v173, 0
	v_mov_b32_e32 v174, 0
	v_mov_b32_e32 v175, 0
	v_mov_b32_e32 v176, 0
	v_mov_b32_e32 v177, 0
	v_mov_b32_e32 v178, 0
	v_mov_b32_e32 v179, 0
	s_mov_b32 s0, 0
	s_mul_i32 s2, s0, 0x90000
	s_add_u32 s12, s38, s2
	s_addc_u32 s13, s39, 0
	s_lshl_b32 s2, s0, 9
	s_add_u32 s14, s36, s2
	s_addc_u32 s15, s37, 0
	global_load_dwordx4 v[2:5], v188, s[12:13]
	global_load_dwordx4 v[6:9], v189, s[12:13]
	global_load_dwordx4 v[10:13], v190, s[12:13]
	global_load_dwordx4 v[14:17], v191, s[12:13]
	global_load_dwordx4 v[18:21], v192, s[12:13]
	global_load_dwordx4 v[22:25], v193, s[12:13]
	global_load_dwordx4 v[26:29], v194, s[12:13]
	global_load_dwordx4 v[30:33], v195, s[12:13]
	global_load_dwordx4 v[34:37], v196, s[14:15]
	global_load_dwordx4 v[38:41], v197, s[14:15]
	s_mov_b32 s0, 1
	s_mul_i32 s2, s0, 0x90000
	s_add_u32 s12, s38, s2
	s_addc_u32 s13, s39, 0
	s_lshl_b32 s2, s0, 9
	s_add_u32 s14, s36, s2
	s_addc_u32 s15, s37, 0
	global_load_dwordx4 v[42:45], v188, s[12:13]
	global_load_dwordx4 v[46:49], v189, s[12:13]
	global_load_dwordx4 v[50:53], v190, s[12:13]
	global_load_dwordx4 v[54:57], v191, s[12:13]
	global_load_dwordx4 v[58:61], v192, s[12:13]
	global_load_dwordx4 v[62:65], v193, s[12:13]
	global_load_dwordx4 v[66:69], v194, s[12:13]
	global_load_dwordx4 v[70:73], v195, s[12:13]
	global_load_dwordx4 v[74:77], v196, s[14:15]
	global_load_dwordx4 v[78:81], v197, s[14:15]
	s_mov_b32 s0, 2
	s_mul_i32 s2, s0, 0x90000
	s_add_u32 s12, s38, s2
	s_addc_u32 s13, s39, 0
	s_lshl_b32 s2, s0, 9
	s_add_u32 s14, s36, s2
	s_addc_u32 s15, s37, 0
	global_load_dwordx4 v[82:85], v188, s[12:13]
	global_load_dwordx4 v[86:89], v189, s[12:13]
	global_load_dwordx4 v[90:93], v190, s[12:13]
	global_load_dwordx4 v[94:97], v191, s[12:13]
	global_load_dwordx4 v[98:101], v192, s[12:13]
	global_load_dwordx4 v[102:105], v193, s[12:13]
	global_load_dwordx4 v[106:109], v194, s[12:13]
	global_load_dwordx4 v[110:113], v195, s[12:13]
	global_load_dwordx4 v[114:117], v196, s[14:15]
	global_load_dwordx4 v[118:121], v197, s[14:15]
	s_waitcnt lgkmcnt(0)
	s_barrier
.Lhg_scan_loop_s:
	s_add_i32 s0, s22, 3
	s_min_u32 s0, s0, 63
	s_mul_i32 s2, s0, 0x90000
	s_add_u32 s12, s38, s2
	s_addc_u32 s13, s39, 0
	s_lshl_b32 s2, s0, 9
	s_add_u32 s14, s36, s2
	s_addc_u32 s15, s37, 0
	global_load_dwordx4 v[122:125], v188, s[12:13]
	global_load_dwordx4 v[126:129], v189, s[12:13]
	global_load_dwordx4 v[130:133], v190, s[12:13]
	global_load_dwordx4 v[134:137], v191, s[12:13]
	global_load_dwordx4 v[138:141], v192, s[12:13]
	global_load_dwordx4 v[142:145], v193, s[12:13]
	global_load_dwordx4 v[146:149], v194, s[12:13]
	global_load_dwordx4 v[150:153], v195, s[12:13]
	global_load_dwordx4 v[154:157], v196, s[14:15]
	global_load_dwordx4 v[158:161], v197, s[14:15]
	s_waitcnt vmcnt(30)
	v_pk_mul_f32 v[164:165], v[164:165], v[34:35]
	v_pk_mul_f32 v[166:167], v[166:167], v[36:37]
	v_pk_mul_f32 v[168:169], v[168:169], v[34:35]
	v_pk_mul_f32 v[170:171], v[170:171], v[36:37]
	v_pk_mul_f32 v[172:173], v[172:173], v[38:39]
	v_pk_mul_f32 v[174:175], v[174:175], v[40:41]
	v_pk_mul_f32 v[176:177], v[176:177], v[38:39]
	v_pk_mul_f32 v[178:179], v[178:179], v[40:41]
	v_mfma_f32_16x16x32_bf16 v[164:167], v[2:5], v[18:21], v[164:167]
	v_mfma_f32_16x16x32_bf16 v[168:171], v[2:5], v[26:29], v[168:171]
	v_mfma_f32_16x16x32_bf16 v[172:175], v[10:13], v[18:21], v[172:175]
	v_mfma_f32_16x16x32_bf16 v[176:179], v[10:13], v[26:29], v[176:179]
	v_mfma_f32_16x16x32_bf16 v[164:167], v[6:9], v[22:25], v[164:167]
	v_mfma_f32_16x16x32_bf16 v[168:171], v[6:9], v[30:33], v[168:171]
	v_mfma_f32_16x16x32_bf16 v[172:175], v[14:17], v[22:25], v[172:175]
	v_mfma_f32_16x16x32_bf16 v[176:179], v[14:17], v[30:33], v[176:179]
	s_nop 4
	v_cvt_pk_bf16_f32 v180, v164, v165
	v_cvt_pk_bf16_f32 v181, v166, v167
	ds_write_b64 v198, v[180:181] offset:8704
	v_cvt_pk_bf16_f32 v182, v168, v169
	v_cvt_pk_bf16_f32 v183, v170, v171
	ds_write_b64 v198, v[182:183] offset:13056
	v_cvt_pk_bf16_f32 v184, v172, v173
	v_cvt_pk_bf16_f32 v185, v174, v175
	ds_write_b64 v198, v[184:185] offset:8736
	v_cvt_pk_bf16_f32 v186, v176, v177
	v_cvt_pk_bf16_f32 v187, v178, v179
	ds_write_b64 v198, v[186:187] offset:13088
	s_add_i32 s22, s22, 1
	s_waitcnt lgkmcnt(0)
	s_barrier
; __device__ void hg_scan_block(const Params& p, int L, int item) {
;     ...
;   HG_LOAD(A, 0); HG_LOAD(B, 1);
;   __syncthreads();
;   for (int n = 0; n < 63; n += 3) {
;     HG_LOAD(C, n + 2); HG_STEP(A, n);
;     HG_LOAD(A, n + 3); HG_STEP(B, n + 1);
;     if (n + 4 < 64) HG_LOAD(B, n + 4);
;     HG_STEP(C, n + 2);
;   }
;   HG_STEP(A, 63);
	s_add_i32 s0, s22, 3
	s_min_u32 s0, s0, 63
	s_mul_i32 s2, s0, 0x90000
	s_add_u32 s12, s38, s2
	s_addc_u32 s13, s39, 0
	s_lshl_b32 s2, s0, 9
	s_add_u32 s14, s36, s2
	s_addc_u32 s15, s37, 0
	global_load_dwordx4 v[2:5], v188, s[12:13]
	global_load_dwordx4 v[6:9], v189, s[12:13]
	global_load_dwordx4 v[10:13], v190, s[12:13]
	global_load_dwordx4 v[14:17], v191, s[12:13]
	global_load_dwordx4 v[18:21], v192, s[12:13]
	global_load_dwordx4 v[22:25], v193, s[12:13]
	global_load_dwordx4 v[26:29], v194, s[12:13]
	global_load_dwordx4 v[30:33], v195, s[12:13]
	global_load_dwordx4 v[34:37], v196, s[14:15]
	global_load_dwordx4 v[38:41], v197, s[14:15]
	s_waitcnt vmcnt(30)
	v_pk_mul_f32 v[164:165], v[164:165], v[74:75]
	v_pk_mul_f32 v[166:167], v[166:167], v[76:77]
	v_pk_mul_f32 v[168:169], v[168:169], v[74:75]
	v_pk_mul_f32 v[170:171], v[170:171], v[76:77]
	v_pk_mul_f32 v[172:173], v[172:173], v[78:79]
	v_pk_mul_f32 v[174:175], v[174:175], v[80:81]
	v_pk_mul_f32 v[176:177], v[176:177], v[78:79]
	v_pk_mul_f32 v[178:179], v[178:179], v[80:81]
	v_mfma_f32_16x16x32_bf16 v[164:167], v[42:45], v[58:61], v[164:167]
	v_mfma_f32_16x16x32_bf16 v[168:171], v[42:45], v[66:69], v[168:171]
	v_mfma_f32_16x16x32_bf16 v[172:175], v[50:53], v[58:61], v[172:175]
	v_mfma_f32_16x16x32_bf16 v[176:179], v[50:53], v[66:69], v[176:179]
	v_mfma_f32_16x16x32_bf16 v[164:167], v[46:49], v[62:65], v[164:167]
	v_mfma_f32_16x16x32_bf16 v[168:171], v[46:49], v[70:73], v[168:171]
	v_mfma_f32_16x16x32_bf16 v[172:175], v[54:57], v[62:65], v[172:175]
	v_mfma_f32_16x16x32_bf16 v[176:179], v[54:57], v[70:73], v[176:179]
	s_nop 4
	v_cvt_pk_bf16_f32 v180, v164, v165
	v_cvt_pk_bf16_f32 v181, v166, v167
	ds_write_b64 v198, v[180:181] offset:0
	v_cvt_pk_bf16_f32 v182, v168, v169
	v_cvt_pk_bf16_f32 v183, v170, v171
	ds_write_b64 v198, v[182:183] offset:4352
	v_cvt_pk_bf16_f32 v184, v172, v173
	v_cvt_pk_bf16_f32 v185, v174, v175
	ds_write_b64 v198, v[184:185] offset:32
	v_cvt_pk_bf16_f32 v186, v176, v177
	v_cvt_pk_bf16_f32 v187, v178, v179
	ds_write_b64 v198, v[186:187] offset:4384
	s_add_i32 s22, s22, 1
	s_waitcnt lgkmcnt(0)
	s_barrier
	s_add_i32 s0, s22, 3
	s_min_u32 s0, s0, 63
	s_mul_i32 s2, s0, 0x90000
	s_add_u32 s12, s38, s2
	s_addc_u32 s13, s39, 0
	s_lshl_b32 s2, s0, 9
	s_add_u32 s14, s36, s2
	s_addc_u32 s15, s37, 0
	global_load_dwordx4 v[42:45], v188, s[12:13]
	global_load_dwordx4 v[46:49], v189, s[12:13]
	global_load_dwordx4 v[50:53], v190, s[12:13]
	global_load_dwordx4 v[54:57], v191, s[12:13]
	global_load_dwordx4 v[58:61], v192, s[12:13]
	global_load_dwordx4 v[62:65], v193, s[12:13]
	global_load_dwordx4 v[66:69], v194, s[12:13]
	global_load_dwordx4 v[70:73], v195, s[12:13]
	global_load_dwordx4 v[74:77], v196, s[14:15]
	global_load_dwordx4 v[78:81], v197, s[14:15]
	s_waitcnt vmcnt(30)
	v_pk_mul_f32 v[164:165], v[164:165], v[114:115]
	v_pk_mul_f32 v[166:167], v[166:167], v[116:117]
	v_pk_mul_f32 v[168:169], v[168:169], v[114:115]
	v_pk_mul_f32 v[170:171], v[170:171], v[116:117]
	v_pk_mul_f32 v[172:173], v[172:173], v[118:119]
	v_pk_mul_f32 v[174:175], v[174:175], v[120:121]
	v_pk_mul_f32 v[176:177], v[176:177], v[118:119]
	v_pk_mul_f32 v[178:179], v[178:179], v[120:121]
	v_mfma_f32_16x16x32_bf16 v[164:167], v[82:85], v[98:101], v[164:167]
	v_mfma_f32_16x16x32_bf16 v[168:171], v[82:85], v[106:109], v[168:171]
	v_mfma_f32_16x16x32_bf16 v[172:175], v[90:93], v[98:101], v[172:175]
	v_mfma_f32_16x16x32_bf16 v[176:179], v[90:93], v[106:109], v[176:179]
	v_mfma_f32_16x16x32_bf16 v[164:167], v[86:89], v[102:105], v[164:167]
	v_mfma_f32_16x16x32_bf16 v[168:171], v[86:89], v[110:113], v[168:171]
	v_mfma_f32_16x16x32_bf16 v[172:175], v[94:97], v[102:105], v[172:175]
	v_mfma_f32_16x16x32_bf16 v[176:179], v[94:97], v[110:113], v[176:179]
	s_nop 4
	v_cvt_pk_bf16_f32 v180, v164, v165
	v_cvt_pk_bf16_f32 v181, v166, v167
	ds_write_b64 v198, v[180:181] offset:8704
	v_cvt_pk_bf16_f32 v182, v168, v169
	v_cvt_pk_bf16_f32 v183, v170, v171
	ds_write_b64 v198, v[182:183] offset:13056
	v_cvt_pk_bf16_f32 v184, v172, v173
	v_cvt_pk_bf16_f32 v185, v174, v175
	ds_write_b64 v198, v[184:185] offset:8736
	v_cvt_pk_bf16_f32 v186, v176, v177
	v_cvt_pk_bf16_f32 v187, v178, v179
	ds_write_b64 v198, v[186:187] offset:13088
	s_add_i32 s22, s22, 1
	s_waitcnt lgkmcnt(0)
	s_barrier
	s_add_i32 s0, s22, 3
	s_min_u32 s0, s0, 63
	s_mul_i32 s2, s0, 0x90000
	s_add_u32 s12, s38, s2
	s_addc_u32 s13, s39, 0
	s_lshl_b32 s2, s0, 9
	s_add_u32 s14, s36, s2
	s_addc_u32 s15, s37, 0
	global_load_dwordx4 v[82:85], v188, s[12:13]
	global_load_dwordx4 v[86:89], v189, s[12:13]
	global_load_dwordx4 v[90:93], v190, s[12:13]
	global_load_dwordx4 v[94:97], v191, s[12:13]
	global_load_dwordx4 v[98:101], v192, s[12:13]
	global_load_dwordx4 v[102:105], v193, s[12:13]
	global_load_dwordx4 v[106:109], v194, s[12:13]
	global_load_dwordx4 v[110:113], v195, s[12:13]
	global_load_dwordx4 v[114:117], v196, s[14:15]
	global_load_dwordx4 v[118:121], v197, s[14:15]
	s_waitcnt vmcnt(30)
	v_pk_mul_f32 v[164:165], v[164:165], v[154:155]
	v_pk_mul_f32 v[166:167], v[166:167], v[156:157]
	v_pk_mul_f32 v[168:169], v[168:169], v[154:155]
	v_pk_mul_f32 v[170:171], v[170:171], v[156:157]
	v_pk_mul_f32 v[172:173], v[172:173], v[158:159]
	v_pk_mul_f32 v[174:175], v[174:175], v[160:161]
	v_pk_mul_f32 v[176:177], v[176:177], v[158:159]
	v_pk_mul_f32 v[178:179], v[178:179], v[160:161]
	v_mfma_f32_16x16x32_bf16 v[164:167], v[122:125], v[138:141], v[164:167]
	v_mfma_f32_16x16x32_bf16 v[168:171], v[122:125], v[146:149], v[168:171]
	v_mfma_f32_16x16x32_bf16 v[172:175], v[130:133], v[138:141], v[172:175]
	v_mfma_f32_16x16x32_bf16 v[176:179], v[130:133], v[146:149], v[176:179]
	v_mfma_f32_16x16x32_bf16 v[164:167], v[126:129], v[142:145], v[164:167]
	v_mfma_f32_16x16x32_bf16 v[168:171], v[126:129], v[150:153], v[168:171]
	v_mfma_f32_16x16x32_bf16 v[172:175], v[134:137], v[142:145], v[172:175]
	v_mfma_f32_16x16x32_bf16 v[176:179], v[134:137], v[150:153], v[176:179]
	s_nop 4
	v_cvt_pk_bf16_f32 v180, v164, v165
	v_cvt_pk_bf16_f32 v181, v166, v167
	ds_write_b64 v198, v[180:181] offset:0
	v_cvt_pk_bf16_f32 v182, v168, v169
	v_cvt_pk_bf16_f32 v183, v170, v171
	ds_write_b64 v198, v[182:183] offset:4352
	v_cvt_pk_bf16_f32 v184, v172, v173
	v_cvt_pk_bf16_f32 v185, v174, v175
	ds_write_b64 v198, v[184:185] offset:32
	v_cvt_pk_bf16_f32 v186, v176, v177
	v_cvt_pk_bf16_f32 v187, v178, v179
	ds_write_b64 v198, v[186:187] offset:4384
	s_add_i32 s22, s22, 1
	s_waitcnt lgkmcnt(0)
	s_barrier
	s_cmp_lt_u32 s22, 64
	s_cbranch_scc1 .Lhg_scan_loop_s
	s_branch .LBB0_259
.LBB0_268:
	s_and_b64 vcc, exec, s[12:13]
	s_cbranch_vccz .LBB0_259
	s_branch .LBB0_270
.LBB0_270:
	v_mbcnt_lo_u32_b32 v0, -1, 0
	v_mbcnt_hi_u32_b32 v0, -1, v0
	s_movk_i32 s1, 0x1100
	v_or_b32_e32 v106, s33, v0
	s_waitcnt vmcnt(0) lgkmcnt(0)
	v_cmp_gt_i32_e32 vcc, s1, v106
	s_barrier
	s_and_saveexec_b64 s[12:13], vcc
	s_cbranch_execz .LBB0_273
	v_add_u32_e32 v0, 0xfffffe00, v106
	v_lshl_add_u32 v2, v106, 1, 0
	s_mov_b64 s[14:15], 0
